# SWIGLU epilogue in one pass on the accumulator layout: silu(a)*b formed in registers, only the 64x64 result staged through LDS (half the LDS traffic)
# speedup vs baseline: 1.0234x; 1.0055x over previous
; DI int crow(int i, int hh) { return (i & 3) + 8 * (i >> 2) + 4 * hh; }
; DI void epi_slab(const GemmCfg c, const f32x16 (&acc)[4], float* sW, const float* rss, const size_t row0, const int g, const int lane,
;                  float* const g_h, u16* const g_hb, float* const g_out, const int final_out) {
;   int ln_ = lane;
;   asm volatile("" : "+v"(ln_));
;   const int l31 = ln_ & 31, hh = ln_ >> 5;
; #pragma unroll
;   for (int nb = 0; nb < 4; ++nb)
; #pragma unroll
;     for (int i = 0; i < 16; ++i) sW[crow(i, hh) * 132 + nb * 32 + l31] = acc[nb][i];
;   asm volatile("s_waitcnt lgkmcnt(0)" ::: "memory");
;   const int K = c.K;
;   const float invK = 1.0f / (float)K;
;   if (c.epi == EPI_SWIGLU) {
; DI void gemm_run(const GemmCfg c, char* smem, float* const g_h, u16* const g_hb, float* const g_out, const int final_out) {
;     ...
;     for (int mb = 0; mb < 2; ++mb) {
;       const size_t row0 = (size_t)tm * 256 + wm * 64 + mb * 32;
;       if (row0 < (size_t)M) epi_slab(c, acc[mb], sW, s_rowss + wm * 64 + mb * 32, row0, tn * 2 + wn, lane, g_h, g_hb, g_out, final_out);
.LBB0_124:
	s_ashr_i32 s79, s78, 31
	s_lshl_b64 s[4:5], s[78:79], 8
	s_add_u32 s6, s4, s86
	s_addc_u32 s7, s5, s87
	s_lshl_b32 s1, s49, 1
	s_or_b32 s8, s1, s75
	s_lshl_b32 s64, s8, 7
	s_cmp_gt_i32 s8, 1
	s_cselect_b64 s[84:85], -1, 0
	s_cmp_gt_u32 s1, 3
	s_cselect_b64 s[26:27], -1, 0
	s_cmp_eq_u32 s8, 4
	s_cselect_b64 s[70:71], -1, 0
	s_cmp_lt_i32 s8, s20
	s_cselect_b64 s[72:73], -1, 0
	s_cmp_lt_i32 s8, 8
	s_cselect_b64 vcc, -1, 0
	v_mov_b32_e32 v128, 0x3e38aa3b
	v_cndmask_b32_e32 v130, 1.0, v128, vcc
	s_and_b64 s[8:9], vcc, exec
	s_waitcnt lgkmcnt(0)
	v_mov_b64_e32 v[128:129], 0x4080
	s_cselect_b32 s8, 0, 0x100
	v_cmp_lt_u64_e64 s[44:45], s[6:7], v[128:129]
	v_mov_b64_e32 v[128:129], 0x407f
	s_add_u32 s58, s66, s8
	v_cmp_gt_u64_e32 vcc, s[6:7], v[128:129]
	s_addc_u32 s59, s67, 0
	s_barrier
	s_cbranch_vccnz .LBB0_279
	s_cmp_eq_u32 s52, 0
	s_cbranch_scc1 .Lswg2
	v_mov_b32_e32 v131, v185
	s_movk_i32 s8, 0x210
	v_ashrrev_i32_e32 v128, 5, v131
	v_and_b32_e32 v132, 31, v131
	v_mul_lo_u32 v133, v128, s8
	v_lshlrev_b32_e32 v129, 2, v132
	v_lshlrev_b32_e32 v134, 2, v133
	v_add3_u32 v129, s53, v129, v134
	v_lshrrev_b32_e32 v242, 4, v131
	v_mul_u32_u24_e32 v242, 0x840, v242
	v_and_b32_e32 v243, 15, v131
	v_lshl_add_u32 v242, v243, 2, v242
	v_add_u32_e32 v234, s53, v242
	v_add_u32_e32 v235, 0x210, v234
	v_add_u32_e32 v236, 0x420, v234
	v_add_u32_e32 v237, 0x630, v234
	v_add_u32_e32 v238, 0x2100, v234
	v_add_u32_e32 v239, 0x2310, v234
	v_add_u32_e32 v240, 0x2520, v234
	v_add_u32_e32 v241, 0x2730, v234
	ds_write2_b32 v234, v64, v68 offset1:16
	ds_write2_b32 v234, v72, v76 offset0:32 offset1:48
	ds_write2_b32 v234, v80, v84 offset0:64 offset1:80
	ds_write2_b32 v234, v88, v92 offset0:96 offset1:112
	ds_write2_b32 v235, v65, v69 offset1:16
	ds_write2_b32 v235, v73, v77 offset0:32 offset1:48
	ds_write2_b32 v235, v81, v85 offset0:64 offset1:80
	ds_write2_b32 v235, v89, v93 offset0:96 offset1:112
	ds_write2_b32 v236, v66, v70 offset1:16
	ds_write2_b32 v236, v74, v78 offset0:32 offset1:48
	ds_write2_b32 v236, v82, v86 offset0:64 offset1:80
	ds_write2_b32 v236, v90, v94 offset0:96 offset1:112
	ds_write2_b32 v237, v67, v71 offset1:16
	ds_write2_b32 v237, v75, v79 offset0:32 offset1:48
	ds_write2_b32 v237, v83, v87 offset0:64 offset1:80
	ds_write2_b32 v237, v91, v95 offset0:96 offset1:112
	ds_write2_b32 v238, v96, v100 offset1:16
	ds_write2_b32 v238, v104, v108 offset0:32 offset1:48
	ds_write2_b32 v238, v112, v116 offset0:64 offset1:80
	ds_write2_b32 v238, v120, v124 offset0:96 offset1:112
	ds_write2_b32 v239, v97, v101 offset1:16
	ds_write2_b32 v239, v105, v109 offset0:32 offset1:48
	ds_write2_b32 v239, v113, v117 offset0:64 offset1:80
	ds_write2_b32 v239, v121, v125 offset0:96 offset1:112
	ds_write2_b32 v240, v98, v102 offset1:16
	ds_write2_b32 v240, v106, v110 offset0:32 offset1:48
	ds_write2_b32 v240, v114, v118 offset0:64 offset1:80
	ds_write2_b32 v240, v122, v126 offset0:96 offset1:112
	ds_write2_b32 v241, v99, v103 offset1:16
	ds_write2_b32 v241, v107, v111 offset0:32 offset1:48
	ds_write2_b32 v241, v115, v119 offset0:64 offset1:80
	ds_write2_b32 v241, v123, v127 offset0:96 offset1:112
	v_add_u32_e32 v64, 0x3800, v129
	v_add_u32_e32 v65, 0x1000, v129
	v_add_u32_e32 v66, 0x1400, v129
	v_add_u32_e32 v67, 0x2000, v129
	v_add_u32_e32 v68, 0x2400, v129
	v_add_u32_e32 v70, 0x3400, v129
	v_add_u32_e32 v69, 0x3000, v129
	v_add_u32_e32 v71, 0x3600, v129
	s_waitcnt lgkmcnt(0)
	s_mov_b64 s[22:23], -1
	s_mov_b64 s[50:51], 0
	s_cmp_lt_i32 s52, 1
	s_mov_b64 s[14:15], 0
	s_cbranch_scc1 .LBB0_272
	s_cmp_eq_u32 s52, 1
	s_mov_b64 s[14:15], -1
	s_cbranch_scc0 .LBB0_192
; DI void epi_slab(const GemmCfg c, const f32x16 (&acc)[4], float* sW, const float* rss, const size_t row0, const int g, const int lane,
;                  float* const g_h, u16* const g_hb, float* const g_out, const int final_out) {
;     ...
;     const int c4 = l31 * 4;
;     const int col = g * 128 + c4;
;     const float sc = (K == DFF ? 0.5f : 1.f);
; #pragma unroll
;     for (int hb_ = 0; hb_ < 2; ++hb_) {
;       f32x4 hv[8];
; #pragma unroll
;       for (int i8 = 0; i8 < 8; ++i8) hv[i8] = *(const f32x4*)(g_h + (row0 + hh + 2 * (hb_ * 8 + i8)) * D + col);
; #pragma unroll
;       for (int i8 = 0; i8 < 8; ++i8) {
;         const int r = hh + 2 * (hb_ * 8 + i8);
;         const size_t row = row0 + r;
;         f32x4 v = *(const f32x4*)(sW + r * 132 + c4);
;         f32x4 o = hv[i8] + v * sc;
;         *(f32x4*)(g_h + row * D + col) = o;
;         *(u32x2*)(g_hb + row * D + col) = MK2(pack2(o[0], o[1]), pack2(o[2], o[3]));
;         if (final_out) {
;           const int b = (int)(row / T), t = (int)(row % T);
;           if (t >= 16) *(f32x4*)(g_out + ((size_t)b * 2048 + (t - 16)) * D + col) = o;
;         }
	v_lshl_or_b32 v98, v132, 2, s64
	v_ashrrev_i32_e32 v129, 31, v128
	v_ashrrev_i32_e32 v99, 31, v98
	v_readlane_b32 s8, v254, 60
	v_lshl_add_u64 v[104:105], s[6:7], 0, v[128:129]
	v_lshlrev_b64 v[106:107], 2, v[98:99]
	v_readlane_b32 s9, v254, 61
	v_lshlrev_b64 v[64:65], 12, v[104:105]
	v_lshl_add_u32 v108, v132, 4, s53
	v_lshl_add_u64 v[96:97], s[8:9], 0, v[106:107]
	v_lshl_add_u64 v[102:103], v[96:97], 0, v[64:65]
	s_movk_i32 s8, 0x2000
	v_add_co_u32_e32 v64, vcc, s8, v102
	s_movk_i32 s8, 0x4000
	s_nop 0
	v_addc_co_u32_e32 v65, vcc, 0, v103, vcc
	global_load_dwordx4 v[92:95], v[102:103], off
	global_load_dwordx4 v[88:91], v[64:65], off
	v_add_co_u32_e32 v64, vcc, s8, v102
	s_movk_i32 s8, 0x6000
	s_nop 0
	v_addc_co_u32_e32 v65, vcc, 0, v103, vcc
	v_add_co_u32_e32 v66, vcc, s8, v102
	s_mov_b32 s8, 0x8000
	s_nop 0
	v_addc_co_u32_e32 v67, vcc, 0, v103, vcc
	global_load_dwordx4 v[84:87], v[64:65], off
	global_load_dwordx4 v[80:83], v[66:67], off
	v_add_co_u32_e32 v64, vcc, s8, v102
	s_mov_b32 s8, 0xa000
	s_nop 0
	v_addc_co_u32_e32 v65, vcc, 0, v103, vcc
	v_add_co_u32_e32 v66, vcc, s8, v102
	s_mov_b32 s8, 0xc000
	s_nop 0
	v_addc_co_u32_e32 v67, vcc, 0, v103, vcc
	global_load_dwordx4 v[76:79], v[64:65], off
	global_load_dwordx4 v[72:75], v[66:67], off
	v_add_co_u32_e32 v64, vcc, s8, v102
	s_mov_b32 s8, 0xe000
	s_nop 0
	v_addc_co_u32_e32 v65, vcc, 0, v103, vcc
	v_add_co_u32_e32 v66, vcc, s8, v102
	v_add_u32_e32 v100, v108, v133
	s_nop 0
	v_addc_co_u32_e32 v67, vcc, 0, v103, vcc
	global_load_dwordx4 v[68:71], v[64:65], off
	s_nop 0
	global_load_dwordx4 v[64:67], v[66:67], off
	v_readlane_b32 s8, v255, 3
	ds_read_b128 v[110:113], v100
	v_readlane_b32 s9, v255, 4
	v_mov_b32_e32 v171, v170
	s_waitcnt vmcnt(7) lgkmcnt(0)
	v_pk_fma_f32 v[94:95], v[170:171], v[112:113], v[94:95]
	v_lshl_add_u64 v[100:101], v[98:99], 1, s[8:9]
	v_mov_b32_e32 v148, 0x11f69000
	v_mov_b32_e32 v149, 0
	v_lshl_add_u64 v[146:147], v[148:149], 0, s[8:9]
	v_lshrrev_b32_e32 v148, 6, v98
	v_lshlrev_b32_e32 v148, 2, v148
	v_lshl_add_u64 v[146:147], v[146:147], 0, v[148:149]
	v_mov_b32_e32 v143, 0
	v_readlane_b32 s8, v252, 47
	v_readlane_b32 s9, v252, 48
	v_readlane_b32 s8, v255, 13
	v_readlane_b32 s9, v255, 14
	v_readlane_b32 s22, v252, 61
	v_readlane_b32 s23, v252, 62
	v_pk_fma_f32 v[92:93], v[172:173], v[110:111], v[92:93]
	v_lshlrev_b64 v[110:111], 11, v[104:105]
	v_cndmask_b32_e64 v109, 0, 1, s[8:9]
	v_lshl_add_u64 v[98:99], s[22:23], 0, v[106:107]
	v_cvt_pk_bf16_f32 v106, v92, v93
	v_cvt_pk_bf16_f32 v107, v94, v95
	v_lshrrev_b32_e32 v142, 5, v110
	v_lshl_add_u64 v[110:111], v[100:101], 0, v[110:111]
	v_cmp_ne_u32_e64 s[46:47], 1, v109
	s_andn2_b64 vcc, exec, s[8:9]
	v_readlane_b32 s10, v252, 49
	v_readlane_b32 s11, v252, 50
	v_readlane_b32 s12, v252, 51
	v_readlane_b32 s13, v252, 52
	v_readlane_b32 s14, v252, 53
	v_readlane_b32 s15, v252, 54
	v_readlane_b32 s16, v252, 55
	v_readlane_b32 s17, v252, 56
	v_readlane_b32 s18, v252, 57
	v_readlane_b32 s19, v252, 58
	v_readlane_b32 s20, v252, 59
	v_readlane_b32 s21, v252, 60
	global_store_dwordx4 v[102:103], v[92:95], off
	global_store_dwordx2 v[110:111], v[106:107], off
	v_mov_b32_e32 v141, 0
	v_dot2c_f32_bf16_e32 v141, v106, v106
	v_dot2c_f32_bf16_e32 v141, v107, v107
	s_nop 4
	v_add_f32_dpp v141, v141, v141 quad_perm:[1,0,3,2] row_mask:0xf bank_mask:0xf
	s_nop 1
	v_add_f32_dpp v141, v141, v141 quad_perm:[2,3,0,1] row_mask:0xf bank_mask:0xf
	s_nop 1
	v_add_f32_dpp v141, v141, v141 row_half_mirror row_mask:0xf bank_mask:0xf
	s_nop 1
	v_add_f32_dpp v141, v141, v141 row_mirror row_mask:0xf bank_mask:0xf
	v_lshl_add_u64 v[144:145], v[142:143], 0, v[146:147]
	global_store_dword v[144:145], v141, off
	s_cbranch_vccnz .LBB0_131
	s_mov_b32 s8, 0xe03f80ff
	v_mul_hi_u32 v164, v104, s8
	v_mad_u64_u32 v[106:107], s[14:15], v105, s8, v[164:165]
	v_mov_b32_e32 v164, v107
	v_mov_b32_e32 v107, v165
	s_mov_b32 s8, 0xfe03f80f
	v_mad_u64_u32 v[106:107], s[14:15], v104, s8, v[106:107]
	v_mov_b32_e32 v106, v107
	v_mov_b32_e32 v107, v165
	v_lshl_add_u64 v[106:107], v[164:165], 0, v[106:107]
	v_mad_u64_u32 v[106:107], s[14:15], v105, s8, v[106:107]
	v_alignbit_b32 v109, v107, v106, 11
	s_movk_i32 s8, 0x810
	v_mad_u64_u32 v[110:111], s[14:15], v109, s8, 0
	v_lshrrev_b32_e32 v109, 11, v107
	v_mad_u32_u24 v109, v109, s8, v111
	v_sub_co_u32_e32 v104, vcc, v104, v110
	s_nop 1
	v_subb_co_u32_e32 v105, vcc, v105, v109, vcc
	v_cmp_lt_u64_e32 vcc, 15, v[104:105]
	s_and_saveexec_b64 s[14:15], vcc
	s_cbranch_execz .LBB0_130
	v_lshrrev_b64 v[106:107], 11, v[106:107]
	v_mov_b32_e32 v110, v165
	v_mov_b32_e32 v111, v106
	v_ashrrev_i64 v[106:107], 21, v[110:111]
	v_add_u32_e32 v164, -16, v104
	v_lshl_add_u64 v[104:105], v[106:107], 0, v[164:165]
	v_lshlrev_b64 v[104:105], 12, v[104:105]
	v_lshl_add_u64 v[104:105], v[98:99], 0, v[104:105]
	global_store_dwordx4 v[104:105], v[92:95], off

; DI void epi_slab(const GemmCfg c, const f32x16 (&acc)[4], float* sW, const float* rss, const size_t row0, const int g, const int lane,
;                  float* const g_h, u16* const g_hb, float* const g_out, const int final_out) {
;     ...
;   if (c.epi == EPI_SWIGLU) {
;     const int c4 = (ln_ & 15) * 4;
; #pragma unroll 2
;     for (int it = 0; it < 8; ++it) {
;       const int r = (ln_ >> 4) + 4 * it;
;       const float rs = rsqrtf(rss[r] * invK + 1e-6f);
;       f32x4 a = *(const f32x4*)(sW + r * 132 + c4);
;       f32x4 b = *(const f32x4*)(sW + r * 132 + 64 + c4);
;       float y[4];
; #pragma unroll
;       for (int e = 0; e < 4; ++e) { float av = a[e] * rs, bv = b[e] * rs; y[e] = av * __builtin_amdgcn_rcpf(1.f + __expf(-av)) * bv; }
;       *(u32x2*)(c.o16 + (row0 + r) * DFF + g * 64 + c4) = MK2(pack2(y[0], y[1]), pack2(y[2], y[3]));
;     }
.Lswg2:
	v_and_b32_e32 v128, 15, v185
	v_lshrrev_b32_e32 v129, 4, v185
	s_lshl_b32 s4, s86, 2
	s_add_i32 s4, s4, 0x24000
	v_lshl_add_u32 v130, v129, 4, s4
	ds_read_b128 v[132:135], v130
	ds_read_b128 v[136:139], v130 offset:64
	ds_read_b128 v[140:143], v130 offset:128
	ds_read_b128 v[144:147], v130 offset:192
	s_mul_i32 s4, s86, 0x220
	s_mul_i32 s5, s75, 0x4400
	s_add_i32 s4, s4, s5
	v_mul_u32_u24_e32 v154, 0x440, v129
	v_lshl_add_u32 v154, v128, 2, v154
	v_add_u32_e32 v154, s4, v154
	v_add_u32_e32 v155, 0x1100, v154
	v_add_u32_e32 v156, 0x2200, v154
	v_add_u32_e32 v157, 0x3300, v154
	v_mul_u32_u24_e32 v158, 0x110, v129
	v_lshl_add_u32 v158, v128, 4, v158
	v_add_u32_e32 v158, s4, v158
	v_readlane_b32 s6, v255, 23
	v_readlane_b32 s7, v255, 24
	v_readlane_b32 s5, v255, 25
	s_lshl_b32 s1, s49, 7
	s_nop 0
	s_or_b32 s5, s5, s1
	s_lshl_b32 s5, s5, 1
	s_mul_i32 s1, s78, 0x160000
	s_add_i32 s5, s5, s1
	s_add_u32 s6, s6, s5
	s_addc_u32 s7, s7, 0
	v_mul_u32_u24_e32 v160, 0x1600, v129
	v_lshl_add_u32 v160, v128, 3, v160
	v_mov_b32_e32 v161, 0
	v_lshl_add_u64 v[160:161], v[160:161], 0, s[6:7]
	s_mov_b64 s[8:9], 0
	s_waitcnt lgkmcnt(0)
	v_fmaak_f32 v132, v191, v132, 0x358637bd
	v_fmaak_f32 v133, v191, v133, 0x358637bd
	v_cmp_gt_f32_e32 vcc, s33, v132
	v_cmp_gt_f32_e64 s[14:15], s33, v133
	v_mul_f32_e32 v152, 0x4b800000, v132
	v_mul_f32_e32 v153, 0x4b800000, v133
	v_cndmask_b32_e32 v132, v132, v152, vcc
	v_cndmask_b32_e64 v133, v133, v153, s[14:15]
	v_rsq_f32_e32 v132, v132
	v_rsq_f32_e32 v133, v133
	s_nop 0
	v_mul_f32_e32 v152, 0x45800000, v132
	v_mul_f32_e32 v153, 0x45800000, v133
	v_cndmask_b32_e32 v132, v132, v152, vcc
	v_cndmask_b32_e64 v133, v133, v153, s[14:15]
	v_fmaak_f32 v134, v191, v134, 0x358637bd
	v_fmaak_f32 v135, v191, v135, 0x358637bd
	v_cmp_gt_f32_e32 vcc, s33, v134
	v_cmp_gt_f32_e64 s[14:15], s33, v135
	v_mul_f32_e32 v152, 0x4b800000, v134
	v_mul_f32_e32 v153, 0x4b800000, v135
	v_cndmask_b32_e32 v134, v134, v152, vcc
	v_cndmask_b32_e64 v135, v135, v153, s[14:15]
	v_rsq_f32_e32 v134, v134
	v_rsq_f32_e32 v135, v135
	s_nop 0
	v_mul_f32_e32 v152, 0x45800000, v134
	v_mul_f32_e32 v153, 0x45800000, v135
	v_cndmask_b32_e32 v134, v134, v152, vcc
	v_cndmask_b32_e64 v135, v135, v153, s[14:15]
	v_fmaak_f32 v136, v191, v136, 0x358637bd
	v_fmaak_f32 v137, v191, v137, 0x358637bd
	v_cmp_gt_f32_e32 vcc, s33, v136
	v_cmp_gt_f32_e64 s[14:15], s33, v137
	v_mul_f32_e32 v152, 0x4b800000, v136
	v_mul_f32_e32 v153, 0x4b800000, v137
	v_cndmask_b32_e32 v136, v136, v152, vcc
	v_cndmask_b32_e64 v137, v137, v153, s[14:15]
	v_rsq_f32_e32 v136, v136
	v_rsq_f32_e32 v137, v137
	s_nop 0
	v_mul_f32_e32 v152, 0x45800000, v136
	v_mul_f32_e32 v153, 0x45800000, v137
	v_cndmask_b32_e32 v136, v136, v152, vcc
	v_cndmask_b32_e64 v137, v137, v153, s[14:15]
	v_fmaak_f32 v138, v191, v138, 0x358637bd
	v_fmaak_f32 v139, v191, v139, 0x358637bd
	v_cmp_gt_f32_e32 vcc, s33, v138
	v_cmp_gt_f32_e64 s[14:15], s33, v139
	v_mul_f32_e32 v152, 0x4b800000, v138
	v_mul_f32_e32 v153, 0x4b800000, v139
	v_cndmask_b32_e32 v138, v138, v152, vcc
	v_cndmask_b32_e64 v139, v139, v153, s[14:15]
	v_rsq_f32_e32 v138, v138
	v_rsq_f32_e32 v139, v139
	s_nop 0
	v_mul_f32_e32 v152, 0x45800000, v138
	v_mul_f32_e32 v153, 0x45800000, v139
	v_cndmask_b32_e32 v138, v138, v152, vcc
	v_cndmask_b32_e64 v139, v139, v153, s[14:15]
	v_fmaak_f32 v140, v191, v140, 0x358637bd
	v_fmaak_f32 v141, v191, v141, 0x358637bd
	v_cmp_gt_f32_e32 vcc, s33, v140
	v_cmp_gt_f32_e64 s[14:15], s33, v141
	v_mul_f32_e32 v152, 0x4b800000, v140
	v_mul_f32_e32 v153, 0x4b800000, v141
	v_cndmask_b32_e32 v140, v140, v152, vcc
	v_cndmask_b32_e64 v141, v141, v153, s[14:15]
	v_rsq_f32_e32 v140, v140
	v_rsq_f32_e32 v141, v141
	s_nop 0
	v_mul_f32_e32 v152, 0x45800000, v140
	v_mul_f32_e32 v153, 0x45800000, v141
	v_cndmask_b32_e32 v140, v140, v152, vcc
	v_cndmask_b32_e64 v141, v141, v153, s[14:15]
	v_fmaak_f32 v142, v191, v142, 0x358637bd
	v_fmaak_f32 v143, v191, v143, 0x358637bd
	v_cmp_gt_f32_e32 vcc, s33, v142
	v_cmp_gt_f32_e64 s[14:15], s33, v143
	v_mul_f32_e32 v152, 0x4b800000, v142
	v_mul_f32_e32 v153, 0x4b800000, v143
	v_cndmask_b32_e32 v142, v142, v152, vcc
	v_cndmask_b32_e64 v143, v143, v153, s[14:15]
	v_rsq_f32_e32 v142, v142
	v_rsq_f32_e32 v143, v143
	s_nop 0
	v_mul_f32_e32 v152, 0x45800000, v142
	v_mul_f32_e32 v153, 0x45800000, v143
	v_cndmask_b32_e32 v142, v142, v152, vcc
	v_cndmask_b32_e64 v143, v143, v153, s[14:15]
	v_fmaak_f32 v144, v191, v144, 0x358637bd
	v_fmaak_f32 v145, v191, v145, 0x358637bd
	v_cmp_gt_f32_e32 vcc, s33, v144
	v_cmp_gt_f32_e64 s[14:15], s33, v145
	v_mul_f32_e32 v152, 0x4b800000, v144
	v_mul_f32_e32 v153, 0x4b800000, v145
	v_cndmask_b32_e32 v144, v144, v152, vcc
	v_cndmask_b32_e64 v145, v145, v153, s[14:15]
	v_rsq_f32_e32 v144, v144
	v_rsq_f32_e32 v145, v145
	s_nop 0
	v_mul_f32_e32 v152, 0x45800000, v144
	v_mul_f32_e32 v153, 0x45800000, v145
	v_cndmask_b32_e32 v144, v144, v152, vcc
	v_cndmask_b32_e64 v145, v145, v153, s[14:15]
	v_fmaak_f32 v146, v191, v146, 0x358637bd
	v_fmaak_f32 v147, v191, v147, 0x358637bd
	v_cmp_gt_f32_e32 vcc, s33, v146
	v_cmp_gt_f32_e64 s[14:15], s33, v147
	v_mul_f32_e32 v152, 0x4b800000, v146
	v_mul_f32_e32 v153, 0x4b800000, v147
	v_cndmask_b32_e32 v146, v146, v152, vcc
	v_cndmask_b32_e64 v147, v147, v153, s[14:15]
	v_rsq_f32_e32 v146, v146
	v_rsq_f32_e32 v147, v147
	s_nop 0
	v_mul_f32_e32 v152, 0x45800000, v146
	v_mul_f32_e32 v153, 0x45800000, v147
	v_cndmask_b32_e32 v146, v146, v152, vcc
	v_cndmask_b32_e64 v147, v147, v153, s[14:15]
	v_pk_mul_f32 v[64:65], v[64:65], v[132:133]
	v_pk_mul_f32 v[66:67], v[66:67], v[134:135]
	v_pk_mul_f32 v[80:81], v[80:81], v[132:133]
	v_pk_mul_f32 v[82:83], v[82:83], v[134:135]
; DI void epi_slab(const GemmCfg c, const f32x16 (&acc)[4], float* sW, const float* rss, const size_t row0, const int g, const int lane,
;                  float* const g_h, u16* const g_hb, float* const g_out, const int final_out) {
;     ...
;   if (c.epi == EPI_SWIGLU) {
;     const int c4 = (ln_ & 15) * 4;
; #pragma unroll 2
;     for (int it = 0; it < 8; ++it) {
;       const int r = (ln_ >> 4) + 4 * it;
;       const float rs = rsqrtf(rss[r] * invK + 1e-6f);
;       f32x4 a = *(const f32x4*)(sW + r * 132 + c4);
;       f32x4 b = *(const f32x4*)(sW + r * 132 + 64 + c4);
;       float y[4];
; #pragma unroll
;       for (int e = 0; e < 4; ++e) { float av = a[e] * rs, bv = b[e] * rs; y[e] = av * __builtin_amdgcn_rcpf(1.f + __expf(-av)) * bv; }
;       *(u32x2*)(c.o16 + (row0 + r) * DFF + g * 64 + c4) = MK2(pack2(y[0], y[1]), pack2(y[2], y[3]));
;     }
	v_mul_f32_e32 v148, 0xbfb8aa3b, v64
	v_mul_f32_e32 v149, 0xbfb8aa3b, v65
	v_mul_f32_e32 v150, 0xbfb8aa3b, v66
	v_mul_f32_e32 v151, 0xbfb8aa3b, v67
	v_exp_f32_e32 v148, v148
	v_exp_f32_e32 v149, v149
	v_exp_f32_e32 v150, v150
	v_exp_f32_e32 v151, v151
	v_add_f32_e32 v148, 1.0, v148
	v_add_f32_e32 v149, 1.0, v149
	v_add_f32_e32 v150, 1.0, v150
	v_add_f32_e32 v151, 1.0, v151
	v_rcp_f32_e32 v148, v148
	v_rcp_f32_e32 v149, v149
	v_rcp_f32_e32 v150, v150
	v_rcp_f32_e32 v151, v151
	s_nop 0
	v_pk_mul_f32 v[64:65], v[64:65], v[148:149]
	v_pk_mul_f32 v[66:67], v[66:67], v[150:151]
	v_pk_mul_f32 v[64:65], v[80:81], v[64:65]
	v_pk_mul_f32 v[66:67], v[82:83], v[66:67]
	ds_write2_b32 v154, v64, v65 offset0:0 offset1:68
	ds_write2_b32 v154, v66, v67 offset0:136 offset1:204
	v_pk_mul_f32 v[68:69], v[68:69], v[132:133]
	v_pk_mul_f32 v[70:71], v[70:71], v[134:135]
	v_pk_mul_f32 v[84:85], v[84:85], v[132:133]
	v_pk_mul_f32 v[86:87], v[86:87], v[134:135]
	v_mul_f32_e32 v148, 0xbfb8aa3b, v68
	v_mul_f32_e32 v149, 0xbfb8aa3b, v69
	v_mul_f32_e32 v150, 0xbfb8aa3b, v70
	v_mul_f32_e32 v151, 0xbfb8aa3b, v71
	v_exp_f32_e32 v148, v148
	v_exp_f32_e32 v149, v149
	v_exp_f32_e32 v150, v150
	v_exp_f32_e32 v151, v151
	v_add_f32_e32 v148, 1.0, v148
	v_add_f32_e32 v149, 1.0, v149
	v_add_f32_e32 v150, 1.0, v150
	v_add_f32_e32 v151, 1.0, v151
	v_rcp_f32_e32 v148, v148
	v_rcp_f32_e32 v149, v149
	v_rcp_f32_e32 v150, v150
	v_rcp_f32_e32 v151, v151
	s_nop 0
	v_pk_mul_f32 v[68:69], v[68:69], v[148:149]
	v_pk_mul_f32 v[70:71], v[70:71], v[150:151]
	v_pk_mul_f32 v[68:69], v[84:85], v[68:69]
	v_pk_mul_f32 v[70:71], v[86:87], v[70:71]
	ds_write2_b32 v154, v68, v69 offset0:16 offset1:84
	ds_write2_b32 v154, v70, v71 offset0:152 offset1:220
	v_pk_mul_f32 v[72:73], v[72:73], v[132:133]
	v_pk_mul_f32 v[74:75], v[74:75], v[134:135]
	v_pk_mul_f32 v[88:89], v[88:89], v[132:133]
	v_pk_mul_f32 v[90:91], v[90:91], v[134:135]
	v_mul_f32_e32 v148, 0xbfb8aa3b, v72
	v_mul_f32_e32 v149, 0xbfb8aa3b, v73
	v_mul_f32_e32 v150, 0xbfb8aa3b, v74
	v_mul_f32_e32 v151, 0xbfb8aa3b, v75
	v_exp_f32_e32 v148, v148
	v_exp_f32_e32 v149, v149
	v_exp_f32_e32 v150, v150
	v_exp_f32_e32 v151, v151
	v_add_f32_e32 v148, 1.0, v148
	v_add_f32_e32 v149, 1.0, v149
	v_add_f32_e32 v150, 1.0, v150
	v_add_f32_e32 v151, 1.0, v151
	v_rcp_f32_e32 v148, v148
	v_rcp_f32_e32 v149, v149
	v_rcp_f32_e32 v150, v150
	v_rcp_f32_e32 v151, v151
	s_nop 0
	v_pk_mul_f32 v[72:73], v[72:73], v[148:149]
	v_pk_mul_f32 v[74:75], v[74:75], v[150:151]
	v_pk_mul_f32 v[72:73], v[88:89], v[72:73]
	v_pk_mul_f32 v[74:75], v[90:91], v[74:75]
	ds_write2_b32 v154, v72, v73 offset0:32 offset1:100
	ds_write2_b32 v154, v74, v75 offset0:168 offset1:236
	v_pk_mul_f32 v[76:77], v[76:77], v[132:133]
	v_pk_mul_f32 v[78:79], v[78:79], v[134:135]
	v_pk_mul_f32 v[92:93], v[92:93], v[132:133]
	v_pk_mul_f32 v[94:95], v[94:95], v[134:135]
	v_mul_f32_e32 v148, 0xbfb8aa3b, v76
	v_mul_f32_e32 v149, 0xbfb8aa3b, v77
	v_mul_f32_e32 v150, 0xbfb8aa3b, v78
	v_mul_f32_e32 v151, 0xbfb8aa3b, v79
	v_exp_f32_e32 v148, v148
	v_exp_f32_e32 v149, v149
	v_exp_f32_e32 v150, v150
	v_exp_f32_e32 v151, v151
	v_add_f32_e32 v148, 1.0, v148
	v_add_f32_e32 v149, 1.0, v149
	v_add_f32_e32 v150, 1.0, v150
	v_add_f32_e32 v151, 1.0, v151
	v_rcp_f32_e32 v148, v148
	v_rcp_f32_e32 v149, v149
	v_rcp_f32_e32 v150, v150
	v_rcp_f32_e32 v151, v151
	s_nop 0
	v_pk_mul_f32 v[76:77], v[76:77], v[148:149]
	v_pk_mul_f32 v[78:79], v[78:79], v[150:151]
	v_pk_mul_f32 v[76:77], v[92:93], v[76:77]
	v_pk_mul_f32 v[78:79], v[94:95], v[78:79]
	ds_write2_b32 v154, v76, v77 offset0:48 offset1:116
	ds_write2_b32 v154, v78, v79 offset0:184 offset1:252
	v_pk_mul_f32 v[96:97], v[96:97], v[136:137]
	v_pk_mul_f32 v[98:99], v[98:99], v[138:139]
	v_pk_mul_f32 v[112:113], v[112:113], v[136:137]
	v_pk_mul_f32 v[114:115], v[114:115], v[138:139]
	v_mul_f32_e32 v148, 0xbfb8aa3b, v96
	v_mul_f32_e32 v149, 0xbfb8aa3b, v97
	v_mul_f32_e32 v150, 0xbfb8aa3b, v98
	v_mul_f32_e32 v151, 0xbfb8aa3b, v99
	v_exp_f32_e32 v148, v148
	v_exp_f32_e32 v149, v149
	v_exp_f32_e32 v150, v150
	v_exp_f32_e32 v151, v151
	v_add_f32_e32 v148, 1.0, v148
	v_add_f32_e32 v149, 1.0, v149
	v_add_f32_e32 v150, 1.0, v150
	v_add_f32_e32 v151, 1.0, v151
	v_rcp_f32_e32 v148, v148
	v_rcp_f32_e32 v149, v149
	v_rcp_f32_e32 v150, v150
	v_rcp_f32_e32 v151, v151
	s_nop 0
	v_pk_mul_f32 v[96:97], v[96:97], v[148:149]
	v_pk_mul_f32 v[98:99], v[98:99], v[150:151]
	v_pk_mul_f32 v[96:97], v[112:113], v[96:97]
	v_pk_mul_f32 v[98:99], v[114:115], v[98:99]
	ds_write2_b32 v155, v96, v97 offset0:0 offset1:68
	ds_write2_b32 v155, v98, v99 offset0:136 offset1:204
	v_pk_mul_f32 v[100:101], v[100:101], v[136:137]
	v_pk_mul_f32 v[102:103], v[102:103], v[138:139]
	v_pk_mul_f32 v[116:117], v[116:117], v[136:137]
	v_pk_mul_f32 v[118:119], v[118:119], v[138:139]
	v_mul_f32_e32 v148, 0xbfb8aa3b, v100
	v_mul_f32_e32 v149, 0xbfb8aa3b, v101
	v_mul_f32_e32 v150, 0xbfb8aa3b, v102
	v_mul_f32_e32 v151, 0xbfb8aa3b, v103
	v_exp_f32_e32 v148, v148
	v_exp_f32_e32 v149, v149
	v_exp_f32_e32 v150, v150
	v_exp_f32_e32 v151, v151
	v_add_f32_e32 v148, 1.0, v148
	v_add_f32_e32 v149, 1.0, v149
	v_add_f32_e32 v150, 1.0, v150
	v_add_f32_e32 v151, 1.0, v151
	v_rcp_f32_e32 v148, v148
	v_rcp_f32_e32 v149, v149
	v_rcp_f32_e32 v150, v150
	v_rcp_f32_e32 v151, v151
	s_nop 0
	v_pk_mul_f32 v[100:101], v[100:101], v[148:149]
	v_pk_mul_f32 v[102:103], v[102:103], v[150:151]
	v_pk_mul_f32 v[100:101], v[116:117], v[100:101]
	v_pk_mul_f32 v[102:103], v[118:119], v[102:103]
	ds_write2_b32 v155, v100, v101 offset0:16 offset1:84
	ds_write2_b32 v155, v102, v103 offset0:152 offset1:220
	v_pk_mul_f32 v[104:105], v[104:105], v[136:137]
; DI void epi_slab(const GemmCfg c, const f32x16 (&acc)[4], float* sW, const float* rss, const size_t row0, const int g, const int lane,
;                  float* const g_h, u16* const g_hb, float* const g_out, const int final_out) {
;     ...
;   if (c.epi == EPI_SWIGLU) {
;     const int c4 = (ln_ & 15) * 4;
; #pragma unroll 2
;     for (int it = 0; it < 8; ++it) {
;       const int r = (ln_ >> 4) + 4 * it;
;       const float rs = rsqrtf(rss[r] * invK + 1e-6f);
;       f32x4 a = *(const f32x4*)(sW + r * 132 + c4);
;       f32x4 b = *(const f32x4*)(sW + r * 132 + 64 + c4);
;       float y[4];
; #pragma unroll
;       for (int e = 0; e < 4; ++e) { float av = a[e] * rs, bv = b[e] * rs; y[e] = av * __builtin_amdgcn_rcpf(1.f + __expf(-av)) * bv; }
;       *(u32x2*)(c.o16 + (row0 + r) * DFF + g * 64 + c4) = MK2(pack2(y[0], y[1]), pack2(y[2], y[3]));
;     }
	v_pk_mul_f32 v[106:107], v[106:107], v[138:139]
	v_pk_mul_f32 v[120:121], v[120:121], v[136:137]
	v_pk_mul_f32 v[122:123], v[122:123], v[138:139]
	v_mul_f32_e32 v148, 0xbfb8aa3b, v104
	v_mul_f32_e32 v149, 0xbfb8aa3b, v105
	v_mul_f32_e32 v150, 0xbfb8aa3b, v106
	v_mul_f32_e32 v151, 0xbfb8aa3b, v107
	v_exp_f32_e32 v148, v148
	v_exp_f32_e32 v149, v149
	v_exp_f32_e32 v150, v150
	v_exp_f32_e32 v151, v151
	v_add_f32_e32 v148, 1.0, v148
	v_add_f32_e32 v149, 1.0, v149
	v_add_f32_e32 v150, 1.0, v150
	v_add_f32_e32 v151, 1.0, v151
	v_rcp_f32_e32 v148, v148
	v_rcp_f32_e32 v149, v149
	v_rcp_f32_e32 v150, v150
	v_rcp_f32_e32 v151, v151
	s_nop 0
	v_pk_mul_f32 v[104:105], v[104:105], v[148:149]
	v_pk_mul_f32 v[106:107], v[106:107], v[150:151]
	v_pk_mul_f32 v[104:105], v[120:121], v[104:105]
	v_pk_mul_f32 v[106:107], v[122:123], v[106:107]
	ds_write2_b32 v155, v104, v105 offset0:32 offset1:100
	ds_write2_b32 v155, v106, v107 offset0:168 offset1:236
	v_pk_mul_f32 v[108:109], v[108:109], v[136:137]
	v_pk_mul_f32 v[110:111], v[110:111], v[138:139]
	v_pk_mul_f32 v[124:125], v[124:125], v[136:137]
	v_pk_mul_f32 v[126:127], v[126:127], v[138:139]
	v_mul_f32_e32 v148, 0xbfb8aa3b, v108
	v_mul_f32_e32 v149, 0xbfb8aa3b, v109
	v_mul_f32_e32 v150, 0xbfb8aa3b, v110
	v_mul_f32_e32 v151, 0xbfb8aa3b, v111
	v_exp_f32_e32 v148, v148
	v_exp_f32_e32 v149, v149
	v_exp_f32_e32 v150, v150
	v_exp_f32_e32 v151, v151
	v_add_f32_e32 v148, 1.0, v148
	v_add_f32_e32 v149, 1.0, v149
	v_add_f32_e32 v150, 1.0, v150
	v_add_f32_e32 v151, 1.0, v151
	v_rcp_f32_e32 v148, v148
	v_rcp_f32_e32 v149, v149
	v_rcp_f32_e32 v150, v150
	v_rcp_f32_e32 v151, v151
	s_nop 0
	v_pk_mul_f32 v[108:109], v[108:109], v[148:149]
	v_pk_mul_f32 v[110:111], v[110:111], v[150:151]
	v_pk_mul_f32 v[108:109], v[124:125], v[108:109]
	v_pk_mul_f32 v[110:111], v[126:127], v[110:111]
	ds_write2_b32 v155, v108, v109 offset0:48 offset1:116
	ds_write2_b32 v155, v110, v111 offset0:184 offset1:252
	v_pk_mul_f32 v[0:1], v[0:1], v[140:141]
	v_pk_mul_f32 v[2:3], v[2:3], v[142:143]
	v_pk_mul_f32 v[16:17], v[16:17], v[140:141]
	v_pk_mul_f32 v[18:19], v[18:19], v[142:143]
	v_mul_f32_e32 v148, 0xbfb8aa3b, v0
	v_mul_f32_e32 v149, 0xbfb8aa3b, v1
	v_mul_f32_e32 v150, 0xbfb8aa3b, v2
	v_mul_f32_e32 v151, 0xbfb8aa3b, v3
	v_exp_f32_e32 v148, v148
	v_exp_f32_e32 v149, v149
	v_exp_f32_e32 v150, v150
	v_exp_f32_e32 v151, v151
	v_add_f32_e32 v148, 1.0, v148
	v_add_f32_e32 v149, 1.0, v149
	v_add_f32_e32 v150, 1.0, v150
	v_add_f32_e32 v151, 1.0, v151
	v_rcp_f32_e32 v148, v148
	v_rcp_f32_e32 v149, v149
	v_rcp_f32_e32 v150, v150
	v_rcp_f32_e32 v151, v151
	s_nop 0
	v_pk_mul_f32 v[0:1], v[0:1], v[148:149]
	v_pk_mul_f32 v[2:3], v[2:3], v[150:151]
	v_pk_mul_f32 v[0:1], v[16:17], v[0:1]
	v_pk_mul_f32 v[2:3], v[18:19], v[2:3]
	ds_write2_b32 v156, v0, v1 offset0:0 offset1:68
	ds_write2_b32 v156, v2, v3 offset0:136 offset1:204
	v_pk_mul_f32 v[4:5], v[4:5], v[140:141]
	v_pk_mul_f32 v[6:7], v[6:7], v[142:143]
	v_pk_mul_f32 v[20:21], v[20:21], v[140:141]
	v_pk_mul_f32 v[22:23], v[22:23], v[142:143]
	v_mul_f32_e32 v148, 0xbfb8aa3b, v4
	v_mul_f32_e32 v149, 0xbfb8aa3b, v5
	v_mul_f32_e32 v150, 0xbfb8aa3b, v6
	v_mul_f32_e32 v151, 0xbfb8aa3b, v7
	v_exp_f32_e32 v148, v148
	v_exp_f32_e32 v149, v149
	v_exp_f32_e32 v150, v150
	v_exp_f32_e32 v151, v151
	v_add_f32_e32 v148, 1.0, v148
	v_add_f32_e32 v149, 1.0, v149
	v_add_f32_e32 v150, 1.0, v150
	v_add_f32_e32 v151, 1.0, v151
	v_rcp_f32_e32 v148, v148
	v_rcp_f32_e32 v149, v149
	v_rcp_f32_e32 v150, v150
	v_rcp_f32_e32 v151, v151
	s_nop 0
	v_pk_mul_f32 v[4:5], v[4:5], v[148:149]
	v_pk_mul_f32 v[6:7], v[6:7], v[150:151]
	v_pk_mul_f32 v[4:5], v[20:21], v[4:5]
	v_pk_mul_f32 v[6:7], v[22:23], v[6:7]
	ds_write2_b32 v156, v4, v5 offset0:16 offset1:84
	ds_write2_b32 v156, v6, v7 offset0:152 offset1:220
	v_pk_mul_f32 v[8:9], v[8:9], v[140:141]
	v_pk_mul_f32 v[10:11], v[10:11], v[142:143]
	v_pk_mul_f32 v[24:25], v[24:25], v[140:141]
	v_pk_mul_f32 v[26:27], v[26:27], v[142:143]
	v_mul_f32_e32 v148, 0xbfb8aa3b, v8
	v_mul_f32_e32 v149, 0xbfb8aa3b, v9
	v_mul_f32_e32 v150, 0xbfb8aa3b, v10
	v_mul_f32_e32 v151, 0xbfb8aa3b, v11
	v_exp_f32_e32 v148, v148
	v_exp_f32_e32 v149, v149
	v_exp_f32_e32 v150, v150
	v_exp_f32_e32 v151, v151
	v_add_f32_e32 v148, 1.0, v148
	v_add_f32_e32 v149, 1.0, v149
	v_add_f32_e32 v150, 1.0, v150
	v_add_f32_e32 v151, 1.0, v151
	v_rcp_f32_e32 v148, v148
	v_rcp_f32_e32 v149, v149
	v_rcp_f32_e32 v150, v150
	v_rcp_f32_e32 v151, v151
	s_nop 0
	v_pk_mul_f32 v[8:9], v[8:9], v[148:149]
	v_pk_mul_f32 v[10:11], v[10:11], v[150:151]
	v_pk_mul_f32 v[8:9], v[24:25], v[8:9]
	v_pk_mul_f32 v[10:11], v[26:27], v[10:11]
	ds_write2_b32 v156, v8, v9 offset0:32 offset1:100
	ds_write2_b32 v156, v10, v11 offset0:168 offset1:236
	v_pk_mul_f32 v[12:13], v[12:13], v[140:141]
	v_pk_mul_f32 v[14:15], v[14:15], v[142:143]
	v_pk_mul_f32 v[28:29], v[28:29], v[140:141]
	v_pk_mul_f32 v[30:31], v[30:31], v[142:143]
	v_mul_f32_e32 v148, 0xbfb8aa3b, v12
	v_mul_f32_e32 v149, 0xbfb8aa3b, v13
	v_mul_f32_e32 v150, 0xbfb8aa3b, v14
	v_mul_f32_e32 v151, 0xbfb8aa3b, v15
	v_exp_f32_e32 v148, v148
	v_exp_f32_e32 v149, v149
	v_exp_f32_e32 v150, v150
	v_exp_f32_e32 v151, v151
	v_add_f32_e32 v148, 1.0, v148
	v_add_f32_e32 v149, 1.0, v149
	v_add_f32_e32 v150, 1.0, v150
	v_add_f32_e32 v151, 1.0, v151
	v_rcp_f32_e32 v148, v148
	v_rcp_f32_e32 v149, v149
	v_rcp_f32_e32 v150, v150
	v_rcp_f32_e32 v151, v151
	s_nop 0
	v_pk_mul_f32 v[12:13], v[12:13], v[148:149]
	v_pk_mul_f32 v[14:15], v[14:15], v[150:151]
	v_pk_mul_f32 v[12:13], v[28:29], v[12:13]
	v_pk_mul_f32 v[14:15], v[30:31], v[14:15]
	ds_write2_b32 v156, v12, v13 offset0:48 offset1:116
; DI void epi_slab(const GemmCfg c, const f32x16 (&acc)[4], float* sW, const float* rss, const size_t row0, const int g, const int lane,
;                  float* const g_h, u16* const g_hb, float* const g_out, const int final_out) {
;     ...
;   if (c.epi == EPI_SWIGLU) {
;     const int c4 = (ln_ & 15) * 4;
; #pragma unroll 2
;     for (int it = 0; it < 8; ++it) {
;       const int r = (ln_ >> 4) + 4 * it;
;       const float rs = rsqrtf(rss[r] * invK + 1e-6f);
;       f32x4 a = *(const f32x4*)(sW + r * 132 + c4);
;       f32x4 b = *(const f32x4*)(sW + r * 132 + 64 + c4);
;       float y[4];
; #pragma unroll
;       for (int e = 0; e < 4; ++e) { float av = a[e] * rs, bv = b[e] * rs; y[e] = av * __builtin_amdgcn_rcpf(1.f + __expf(-av)) * bv; }
;       *(u32x2*)(c.o16 + (row0 + r) * DFF + g * 64 + c4) = MK2(pack2(y[0], y[1]), pack2(y[2], y[3]));
;     }
	ds_write2_b32 v156, v14, v15 offset0:184 offset1:252
	v_pk_mul_f32 v[32:33], v[32:33], v[144:145]
	v_pk_mul_f32 v[34:35], v[34:35], v[146:147]
	v_pk_mul_f32 v[48:49], v[48:49], v[144:145]
	v_pk_mul_f32 v[50:51], v[50:51], v[146:147]
	v_mul_f32_e32 v148, 0xbfb8aa3b, v32
	v_mul_f32_e32 v149, 0xbfb8aa3b, v33
	v_mul_f32_e32 v150, 0xbfb8aa3b, v34
	v_mul_f32_e32 v151, 0xbfb8aa3b, v35
	v_exp_f32_e32 v148, v148
	v_exp_f32_e32 v149, v149
	v_exp_f32_e32 v150, v150
	v_exp_f32_e32 v151, v151
	v_add_f32_e32 v148, 1.0, v148
	v_add_f32_e32 v149, 1.0, v149
	v_add_f32_e32 v150, 1.0, v150
	v_add_f32_e32 v151, 1.0, v151
	v_rcp_f32_e32 v148, v148
	v_rcp_f32_e32 v149, v149
	v_rcp_f32_e32 v150, v150
	v_rcp_f32_e32 v151, v151
	s_nop 0
	v_pk_mul_f32 v[32:33], v[32:33], v[148:149]
	v_pk_mul_f32 v[34:35], v[34:35], v[150:151]
	v_pk_mul_f32 v[32:33], v[48:49], v[32:33]
	v_pk_mul_f32 v[34:35], v[50:51], v[34:35]
	ds_write2_b32 v157, v32, v33 offset0:0 offset1:68
	ds_write2_b32 v157, v34, v35 offset0:136 offset1:204
	v_pk_mul_f32 v[36:37], v[36:37], v[144:145]
	v_pk_mul_f32 v[38:39], v[38:39], v[146:147]
	v_pk_mul_f32 v[52:53], v[52:53], v[144:145]
	v_pk_mul_f32 v[54:55], v[54:55], v[146:147]
	v_mul_f32_e32 v148, 0xbfb8aa3b, v36
	v_mul_f32_e32 v149, 0xbfb8aa3b, v37
	v_mul_f32_e32 v150, 0xbfb8aa3b, v38
	v_mul_f32_e32 v151, 0xbfb8aa3b, v39
	v_exp_f32_e32 v148, v148
	v_exp_f32_e32 v149, v149
	v_exp_f32_e32 v150, v150
	v_exp_f32_e32 v151, v151
	v_add_f32_e32 v148, 1.0, v148
	v_add_f32_e32 v149, 1.0, v149
	v_add_f32_e32 v150, 1.0, v150
	v_add_f32_e32 v151, 1.0, v151
	v_rcp_f32_e32 v148, v148
	v_rcp_f32_e32 v149, v149
	v_rcp_f32_e32 v150, v150
	v_rcp_f32_e32 v151, v151
	s_nop 0
	v_pk_mul_f32 v[36:37], v[36:37], v[148:149]
	v_pk_mul_f32 v[38:39], v[38:39], v[150:151]
	v_pk_mul_f32 v[36:37], v[52:53], v[36:37]
	v_pk_mul_f32 v[38:39], v[54:55], v[38:39]
	ds_write2_b32 v157, v36, v37 offset0:16 offset1:84
	ds_write2_b32 v157, v38, v39 offset0:152 offset1:220
	v_pk_mul_f32 v[40:41], v[40:41], v[144:145]
	v_pk_mul_f32 v[42:43], v[42:43], v[146:147]
	v_pk_mul_f32 v[56:57], v[56:57], v[144:145]
	v_pk_mul_f32 v[58:59], v[58:59], v[146:147]
	v_mul_f32_e32 v148, 0xbfb8aa3b, v40
	v_mul_f32_e32 v149, 0xbfb8aa3b, v41
	v_mul_f32_e32 v150, 0xbfb8aa3b, v42
	v_mul_f32_e32 v151, 0xbfb8aa3b, v43
	v_exp_f32_e32 v148, v148
	v_exp_f32_e32 v149, v149
	v_exp_f32_e32 v150, v150
	v_exp_f32_e32 v151, v151
	v_add_f32_e32 v148, 1.0, v148
	v_add_f32_e32 v149, 1.0, v149
	v_add_f32_e32 v150, 1.0, v150
	v_add_f32_e32 v151, 1.0, v151
	v_rcp_f32_e32 v148, v148
	v_rcp_f32_e32 v149, v149
	v_rcp_f32_e32 v150, v150
	v_rcp_f32_e32 v151, v151
	s_nop 0
	v_pk_mul_f32 v[40:41], v[40:41], v[148:149]
	v_pk_mul_f32 v[42:43], v[42:43], v[150:151]
	v_pk_mul_f32 v[40:41], v[56:57], v[40:41]
	v_pk_mul_f32 v[42:43], v[58:59], v[42:43]
	ds_write2_b32 v157, v40, v41 offset0:32 offset1:100
	ds_write2_b32 v157, v42, v43 offset0:168 offset1:236
	v_pk_mul_f32 v[44:45], v[44:45], v[144:145]
	v_pk_mul_f32 v[46:47], v[46:47], v[146:147]
	v_pk_mul_f32 v[60:61], v[60:61], v[144:145]
	v_pk_mul_f32 v[62:63], v[62:63], v[146:147]
	v_mul_f32_e32 v148, 0xbfb8aa3b, v44
	v_mul_f32_e32 v149, 0xbfb8aa3b, v45
	v_mul_f32_e32 v150, 0xbfb8aa3b, v46
	v_mul_f32_e32 v151, 0xbfb8aa3b, v47
	v_exp_f32_e32 v148, v148
	v_exp_f32_e32 v149, v149
	v_exp_f32_e32 v150, v150
	v_exp_f32_e32 v151, v151
	v_add_f32_e32 v148, 1.0, v148
	v_add_f32_e32 v149, 1.0, v149
	v_add_f32_e32 v150, 1.0, v150
	v_add_f32_e32 v151, 1.0, v151
	v_rcp_f32_e32 v148, v148
	v_rcp_f32_e32 v149, v149
	v_rcp_f32_e32 v150, v150
	v_rcp_f32_e32 v151, v151
	s_nop 0
	v_pk_mul_f32 v[44:45], v[44:45], v[148:149]
	v_pk_mul_f32 v[46:47], v[46:47], v[150:151]
	v_pk_mul_f32 v[44:45], v[60:61], v[44:45]
	v_pk_mul_f32 v[46:47], v[62:63], v[46:47]
	ds_write2_b32 v157, v44, v45 offset0:48 offset1:116
	ds_write2_b32 v157, v46, v47 offset0:184 offset1:252
	s_waitcnt lgkmcnt(0)
	ds_read_b128 v[0:3], v158
	ds_read_b128 v[4:7], v158 offset:1088
	ds_read_b128 v[8:11], v158 offset:2176
	ds_read_b128 v[12:15], v158 offset:3264
	ds_read_b128 v[16:19], v158 offset:4352
	ds_read_b128 v[20:23], v158 offset:5440
	ds_read_b128 v[24:27], v158 offset:6528
	ds_read_b128 v[28:31], v158 offset:7616
	ds_read_b128 v[32:35], v158 offset:8704
	s_waitcnt lgkmcnt(8)
; DI void epi_slab(const GemmCfg c, const f32x16 (&acc)[4], float* sW, const float* rss, const size_t row0, const int g, const int lane,
;                  float* const g_h, u16* const g_hb, float* const g_out, const int final_out) {
;     ...
;       const int r = (ln_ >> 4) + 4 * it;
;       const float rs = rsqrtf(rss[r] * invK + 1e-6f);
;       f32x4 a = *(const f32x4*)(sW + r * 132 + c4);
;       f32x4 b = *(const f32x4*)(sW + r * 132 + 64 + c4);
;       float y[4];
; #pragma unroll
;       for (int e = 0; e < 4; ++e) { float av = a[e] * rs, bv = b[e] * rs; y[e] = av * __builtin_amdgcn_rcpf(1.f + __expf(-av)) * bv; }
;       *(u32x2*)(c.o16 + (row0 + r) * DFF + g * 64 + c4) = MK2(pack2(y[0], y[1]), pack2(y[2], y[3]));
;     }
	v_lshl_add_u64 v[162:163], v[160:161], 0, s[8:9]
	v_cvt_pk_bf16_f32 v0, v0, v1
	v_cvt_pk_bf16_f32 v1, v2, v3
	s_add_u32 s8, s8, 0x5800
	s_addc_u32 s9, s9, 0
	global_store_dwordx2 v[162:163], v[0:1], off
	ds_read_b128 v[36:39], v158 offset:9792
	s_waitcnt lgkmcnt(8)
	v_lshl_add_u64 v[162:163], v[160:161], 0, s[8:9]
	v_cvt_pk_bf16_f32 v4, v4, v5
	v_cvt_pk_bf16_f32 v5, v6, v7
	s_add_u32 s8, s8, 0x5800
	s_addc_u32 s9, s9, 0
	global_store_dwordx2 v[162:163], v[4:5], off
	ds_read_b128 v[40:43], v158 offset:10880
	s_waitcnt lgkmcnt(8)
	v_lshl_add_u64 v[162:163], v[160:161], 0, s[8:9]
	v_cvt_pk_bf16_f32 v8, v8, v9
	v_cvt_pk_bf16_f32 v9, v10, v11
	s_add_u32 s8, s8, 0x5800
	s_addc_u32 s9, s9, 0
	global_store_dwordx2 v[162:163], v[8:9], off
	ds_read_b128 v[44:47], v158 offset:11968
	s_waitcnt lgkmcnt(8)
	v_lshl_add_u64 v[162:163], v[160:161], 0, s[8:9]
	v_cvt_pk_bf16_f32 v12, v12, v13
	v_cvt_pk_bf16_f32 v13, v14, v15
	s_add_u32 s8, s8, 0x5800
	s_addc_u32 s9, s9, 0
	global_store_dwordx2 v[162:163], v[12:13], off
	ds_read_b128 v[48:51], v158 offset:13056
	s_waitcnt lgkmcnt(8)
	v_lshl_add_u64 v[162:163], v[160:161], 0, s[8:9]
	v_cvt_pk_bf16_f32 v16, v16, v17
	v_cvt_pk_bf16_f32 v17, v18, v19
	s_add_u32 s8, s8, 0x5800
	s_addc_u32 s9, s9, 0
	global_store_dwordx2 v[162:163], v[16:17], off
	ds_read_b128 v[52:55], v158 offset:14144
	s_waitcnt lgkmcnt(8)
	v_lshl_add_u64 v[162:163], v[160:161], 0, s[8:9]
	v_cvt_pk_bf16_f32 v20, v20, v21
	v_cvt_pk_bf16_f32 v21, v22, v23
	s_add_u32 s8, s8, 0x5800
	s_addc_u32 s9, s9, 0
	global_store_dwordx2 v[162:163], v[20:21], off
	ds_read_b128 v[56:59], v158 offset:15232
	s_waitcnt lgkmcnt(8)
	v_lshl_add_u64 v[162:163], v[160:161], 0, s[8:9]
	v_cvt_pk_bf16_f32 v24, v24, v25
	v_cvt_pk_bf16_f32 v25, v26, v27
	s_add_u32 s8, s8, 0x5800
	s_addc_u32 s9, s9, 0
	global_store_dwordx2 v[162:163], v[24:25], off
	ds_read_b128 v[60:63], v158 offset:16320
	s_waitcnt lgkmcnt(8)
	v_lshl_add_u64 v[162:163], v[160:161], 0, s[8:9]
	v_cvt_pk_bf16_f32 v28, v28, v29
	v_cvt_pk_bf16_f32 v29, v30, v31
	s_add_u32 s8, s8, 0x5800
	s_addc_u32 s9, s9, 0
	global_store_dwordx2 v[162:163], v[28:29], off
	s_waitcnt lgkmcnt(7)
	v_lshl_add_u64 v[162:163], v[160:161], 0, s[8:9]
	v_cvt_pk_bf16_f32 v32, v32, v33
	v_cvt_pk_bf16_f32 v33, v34, v35
	s_add_u32 s8, s8, 0x5800
	s_addc_u32 s9, s9, 0
	global_store_dwordx2 v[162:163], v[32:33], off
	s_waitcnt lgkmcnt(6)
	v_lshl_add_u64 v[162:163], v[160:161], 0, s[8:9]
	v_cvt_pk_bf16_f32 v36, v36, v37
	v_cvt_pk_bf16_f32 v37, v38, v39
	s_add_u32 s8, s8, 0x5800
	s_addc_u32 s9, s9, 0
	global_store_dwordx2 v[162:163], v[36:37], off
	s_waitcnt lgkmcnt(5)
	v_lshl_add_u64 v[162:163], v[160:161], 0, s[8:9]
	v_cvt_pk_bf16_f32 v40, v40, v41
	v_cvt_pk_bf16_f32 v41, v42, v43
	s_add_u32 s8, s8, 0x5800
	s_addc_u32 s9, s9, 0
	global_store_dwordx2 v[162:163], v[40:41], off
	s_waitcnt lgkmcnt(4)
	v_lshl_add_u64 v[162:163], v[160:161], 0, s[8:9]
	v_cvt_pk_bf16_f32 v44, v44, v45
	v_cvt_pk_bf16_f32 v45, v46, v47
	s_add_u32 s8, s8, 0x5800
	s_addc_u32 s9, s9, 0
	global_store_dwordx2 v[162:163], v[44:45], off
	s_waitcnt lgkmcnt(3)
	v_lshl_add_u64 v[162:163], v[160:161], 0, s[8:9]
	v_cvt_pk_bf16_f32 v48, v48, v49
	v_cvt_pk_bf16_f32 v49, v50, v51
	s_add_u32 s8, s8, 0x5800
	s_addc_u32 s9, s9, 0
	global_store_dwordx2 v[162:163], v[48:49], off
	s_waitcnt lgkmcnt(2)
	v_lshl_add_u64 v[162:163], v[160:161], 0, s[8:9]
	v_cvt_pk_bf16_f32 v52, v52, v53
	v_cvt_pk_bf16_f32 v53, v54, v55
	s_add_u32 s8, s8, 0x5800
	s_addc_u32 s9, s9, 0
	global_store_dwordx2 v[162:163], v[52:53], off
	s_waitcnt lgkmcnt(1)
	v_lshl_add_u64 v[162:163], v[160:161], 0, s[8:9]
	v_cvt_pk_bf16_f32 v56, v56, v57
	v_cvt_pk_bf16_f32 v57, v58, v59
	s_add_u32 s8, s8, 0x5800
	s_addc_u32 s9, s9, 0
	global_store_dwordx2 v[162:163], v[56:57], off
	s_waitcnt lgkmcnt(0)
	v_lshl_add_u64 v[162:163], v[160:161], 0, s[8:9]
	v_cvt_pk_bf16_f32 v60, v60, v61
	v_cvt_pk_bf16_f32 v61, v62, v63
	s_add_u32 s8, s8, 0x5800
	s_addc_u32 s9, s9, 0
	global_store_dwordx2 v[162:163], v[60:61], off
	s_branch .LBB0_108
